# code placement 2: GEMM K-loop heads aligned to 256 bytes, unit-loop heads / PE epilogue head / attention and P0 loops to 64 bytes
# baseline (speedup 1.0000x reference)
; template <class Epi, class Sched, bool ALIGN_EPI = false, bool SP2 = false>
; __device__ __forceinline__ void gemm_phase(PG8_LAS unsigned char* lds, const Gemm g, const Sched& S, const Epi& E) {
;     ...
;     for (;;) {
;         const bool has_next = S.next(ui + 1, nxt);
;         const char* nA = has_next ? (const char*)g.A + (size_t)nxt.pm * tstep + (size_t)nxt.seg * K * 2 : cA; const char* nB = has_next ? (const char*)g.Bt + (size_t)nxt.pn * tstepB + (size_t)nxt.seg * K * 2 : cB;
.LBB0_126:
	s_andn2_b64 vcc, exec, s[36:37]
	s_mov_b32 s84, s50
	s_mov_b32 s76, s48
	s_mov_b64 s[38:39], s[72:73]
	s_mov_b64 s[36:37], s[70:71]
	s_cbranch_vccz .LBB0_169
	.p2align 6

; #define PG8_WAIT_V(n) asm volatile("s_waitcnt vmcnt(" #n ")" ::: "memory")
; #define PG8_BAR __builtin_amdgcn_s_barrier()
; template <class Epi, class Sched, bool ALIGN_EPI = false, bool SP2 = false>
; __device__ __forceinline__ void gemm_phase(PG8_LAS unsigned char* lds, const Gemm g, const Sched& S, const Epi& E) {
;     ...
;     f32x4 acc[2][2][4][2];
; #pragma unroll
;     for (int a = 0; a < 2; ++a)
; #pragma unroll
;         for (int b = 0; b < 2; ++b)
; #pragma unroll
;             for (int m = 0; m < 4; ++m)
; #pragma unroll
;                 for (int n = 0; n < 2; ++n) acc[a][b][m][n] = (f32x4){0.f, 0.f, 0.f, 0.f};
;     bf16x8 At[4][2], B0[2][2], B1[2][2];
;     const char* cA = (const char*)g.A + (size_t)cur.pm * tstep + (size_t)cur.seg * K * 2; const char* cB = (const char*)g.Bt + (size_t)cur.pn * tstepB + (size_t)cur.seg * K * 2;
;     if constexpr (SP2) {
;         PG8_STAGE(PG8_SB(0, 0), cB, voffB); PG8_STAGE(PG8_SB(0, 1), cB + hstepB, voffB); PG8_STAGE(PG8_SA(0, 0), cA, voffA); PG8_STAGE(PG8_SA(0, 1), cA + hstep, voffA);
;         if (wr == 1) PG8_BAR;
;         PG8_WAIT_V(2); PG8_BAR;
;         PG8_STAGE(PG8_SB(1, 0), cB + kstep, voffB); PG8_STAGE(PG8_SA(1, 0), cA + kstep, voffA); PG8_STAGE(PG8_SB(1, 1), cB + hstepB + kstep, voffB);
;         PG8_WAIT_V(6); PG8_BAR;
;     } else {
;         PG8_STAGE(PG8_SB(0, 0), cB, voffB); PG8_STAGE(PG8_SA(0, 0), cA, voffA); PG8_STAGE(PG8_SB(0, 1), cB + hstepB, voffB); PG8_STAGE(PG8_SA(0, 1), cA + hstep, voffA);
;         if (wr == 1) PG8_BAR;
;         PG8_WAIT_V(4); PG8_BAR;
;         PG8_STAGE(PG8_SB(1, 0), cB + kstep, voffB); PG8_STAGE(PG8_SA(1, 0), cA + kstep, voffA); PG8_STAGE(PG8_SB(1, 1), cB + hstepB + kstep, voffB);
;         PG8_WAIT_V(6); PG8_BAR;
;     }
;     for (;;) {
;         const bool has_next = S.next(ui + 1, nxt);
;         const char* nA = has_next ? (const char*)g.A + (size_t)nxt.pm * tstep + (size_t)nxt.seg * K * 2 : cA; const char* nB = has_next ? (const char*)g.Bt + (size_t)nxt.pn * tstepB + (size_t)nxt.seg * K * 2 : cB;
;         for (int t = 0; t < nt; t += 2) {
;             const bool last = (t == nt - 2);
;             const char* a1 = cA + (size_t)(t + 1) * kstep;
;             const char* a2 = last ? nA : cA + (size_t)(t + 2) * kstep; const char* b2 = last ? nB : cB + (size_t)(t + 2) * kstep;
;             const char* a3 = a2 + kstep; const char* b3 = b2 + kstep;
.LBB0_129:
	s_ashr_i32 s49, s48, 31
	s_lshl_b64 s[30:31], s[48:49], 19
	s_add_u32 s70, s90, s30
	s_addc_u32 s71, s91, s31
	s_and_b64 s[30:31], s[66:67], exec
	s_cselect_b32 s49, s71, s37
	s_cselect_b32 s77, s70, s36
	s_ashr_i32 s51, s50, 31
	s_lshl_b64 s[30:31], s[50:51], 19
	s_add_u32 s72, s42, s30
	s_addc_u32 s73, s43, s31
	s_and_b64 s[30:31], s[66:67], exec
	s_cselect_b32 s51, s73, s39
	s_cselect_b32 vcc_lo, s72, s38
	s_add_u32 s36, s36, 0x40080
	s_addc_u32 s37, s37, 0
	s_add_u32 vcc_hi, s38, 0x100
	v_mov_b32_e32 v2, 0
	s_addc_u32 s30, s39, 0
	s_mov_b32 s31, -2
	v_mov_b32_e32 v3, v2
	v_mov_b32_e32 v4, v2
	v_mov_b32_e32 v5, v2
	v_mov_b32_e32 v6, v2
	v_mov_b32_e32 v7, v2
	v_mov_b32_e32 v8, v2
	v_mov_b32_e32 v9, v2
	v_mov_b32_e32 v18, v2
	v_mov_b32_e32 v19, v2
	s_waitcnt lgkmcnt(0)
	v_mov_b32_e32 v20, v2
	v_mov_b32_e32 v21, v2
	v_mov_b32_e32 v22, v2
	v_mov_b32_e32 v23, v2
	v_mov_b32_e32 v24, v2
	v_mov_b32_e32 v25, v2
	v_mov_b32_e32 v34, v2
	v_mov_b32_e32 v35, v2
	v_mov_b32_e32 v36, v2
	v_mov_b32_e32 v37, v2
	v_mov_b32_e32 v38, v2
	v_mov_b32_e32 v39, v2
	v_mov_b32_e32 v40, v2
	v_mov_b32_e32 v41, v2
	v_mov_b32_e32 v50, v2
	v_mov_b32_e32 v51, v2
	v_mov_b32_e32 v52, v2
	v_mov_b32_e32 v53, v2
	v_mov_b32_e32 v54, v2
	v_mov_b32_e32 v55, v2
	v_mov_b32_e32 v56, v2
	v_mov_b32_e32 v57, v2
	v_mov_b32_e32 v10, v2
	v_mov_b32_e32 v11, v2
	v_mov_b32_e32 v12, v2
	v_mov_b32_e32 v13, v2
	v_mov_b32_e32 v14, v2
	v_mov_b32_e32 v15, v2
	v_mov_b32_e32 v16, v2
	v_mov_b32_e32 v17, v2
	v_mov_b32_e32 v26, v2
	v_mov_b32_e32 v27, v2
	v_mov_b32_e32 v28, v2
	v_mov_b32_e32 v29, v2
	v_mov_b32_e32 v30, v2
	v_mov_b32_e32 v31, v2
	v_mov_b32_e32 v32, v2
	v_mov_b32_e32 v33, v2
	v_mov_b32_e32 v42, v2
	v_mov_b32_e32 v43, v2
	v_mov_b32_e32 v44, v2
	v_mov_b32_e32 v45, v2
	v_mov_b32_e32 v46, v2
	v_mov_b32_e32 v47, v2
	v_mov_b32_e32 v48, v2
	v_mov_b32_e32 v49, v2
	v_mov_b32_e32 v58, v2
	v_mov_b32_e32 v59, v2
	v_mov_b32_e32 v60, v2
	v_mov_b32_e32 v61, v2
	v_mov_b32_e32 v62, v2
	v_mov_b32_e32 v63, v2
	v_mov_b32_e32 v64, v2
	v_mov_b32_e32 v65, v2
	v_mov_b32_e32 v68, v2
	v_mov_b32_e32 v69, v2
	v_mov_b32_e32 v70, v2
	v_mov_b32_e32 v71, v2
	v_mov_b32_e32 v72, v2
	v_mov_b32_e32 v73, v2
	v_mov_b32_e32 v74, v2
	v_mov_b32_e32 v75, v2
	v_mov_b32_e32 v84, v2
	v_mov_b32_e32 v85, v2
	v_mov_b32_e32 v86, v2
	v_mov_b32_e32 v87, v2
	v_mov_b32_e32 v88, v2
	v_mov_b32_e32 v89, v2
	v_mov_b32_e32 v90, v2
	v_mov_b32_e32 v91, v2
	v_mov_b32_e32 v100, v2
	v_mov_b32_e32 v101, v2
	v_mov_b32_e32 v102, v2
	v_mov_b32_e32 v103, v2
	v_mov_b32_e32 v104, v2
	v_mov_b32_e32 v105, v2
	v_mov_b32_e32 v106, v2
	v_mov_b32_e32 v107, v2
	v_mov_b32_e32 v116, v2
	v_mov_b32_e32 v117, v2
	v_mov_b32_e32 v118, v2
	v_mov_b32_e32 v119, v2
	v_mov_b32_e32 v120, v2
	v_mov_b32_e32 v121, v2
	v_mov_b32_e32 v122, v2
	v_mov_b32_e32 v123, v2
	v_mov_b32_e32 v76, v2
	v_mov_b32_e32 v77, v2
	v_mov_b32_e32 v78, v2
	v_mov_b32_e32 v79, v2
	v_mov_b32_e32 v80, v2
	v_mov_b32_e32 v81, v2
	v_mov_b32_e32 v82, v2
	v_mov_b32_e32 v83, v2
	v_mov_b32_e32 v92, v2
	v_mov_b32_e32 v93, v2
	v_mov_b32_e32 v94, v2
	v_mov_b32_e32 v95, v2
	v_mov_b32_e32 v96, v2
	v_mov_b32_e32 v97, v2
	v_mov_b32_e32 v98, v2
	v_mov_b32_e32 v99, v2
	v_mov_b32_e32 v108, v2
	v_mov_b32_e32 v109, v2
	v_mov_b32_e32 v110, v2
	v_mov_b32_e32 v111, v2
	v_mov_b32_e32 v112, v2
	v_mov_b32_e32 v113, v2
	v_mov_b32_e32 v114, v2
	v_mov_b32_e32 v115, v2
	v_mov_b32_e32 v124, v2
	v_mov_b32_e32 v125, v2
	v_mov_b32_e32 v126, v2
	v_mov_b32_e32 v127, v2
	v_mov_b32_e32 v128, v2
	v_mov_b32_e32 v129, v2
	v_mov_b32_e32 v130, v2
	v_mov_b32_e32 v131, v2
	.p2align 8

; template <class Epi, class Sched, bool ALIGN_EPI = false, bool SP2 = false>
; __device__ __forceinline__ void gemm_phase(PG8_LAS unsigned char* lds, const Gemm g, const Sched& S, const Epi& E) {
;     ...
;         const bool has_next = S.next(ui + 1, nxt);
;         const char* nA = has_next ? (const char*)g.A + (size_t)nxt.pm * tstep + (size_t)nxt.seg * K * 2 : cA; const char* nB = has_next ? (const char*)g.Bt + (size_t)nxt.pn * tstepB + (size_t)nxt.seg * K * 2 : cB;
;         for (int t = 0; t < nt; t += 2) {
;             const bool last = (t == nt - 2);
;             const char* a1 = cA + (size_t)(t + 1) * kstep;
;             const char* a2 = last ? nA : cA + (size_t)(t + 2) * kstep; const char* b2 = last ? nB : cB + (size_t)(t + 2) * kstep;
;             const char* a3 = a2 + kstep; const char* b3 = b2 + kstep;
.LBB0_515:
	s_ashr_i32 s47, s46, 31
	s_and_b32 s26, s25, 1
	s_lshl_b64 s[30:31], s[46:47], 19
	s_add_u32 s30, s68, s30
	s_addc_u32 s31, s69, s31
	s_lshl_b32 s34, s26, 10
	s_add_u32 s50, s30, s34
	s_addc_u32 s51, s31, 0
	s_and_b64 s[30:31], s[70:71], exec
	s_cselect_b32 s37, s51, s39
	s_cselect_b32 s47, s50, s38
	s_ashr_i32 s49, s48, 31
	s_lshl_b64 s[30:31], s[48:49], 19
	s_add_u32 s30, s56, s30
	s_addc_u32 s31, s57, s31
	s_add_u32 s66, s30, s34
	s_addc_u32 s67, s31, 0
	s_and_b64 s[30:31], s[70:71], exec
	s_cselect_b32 s49, s67, s73
	s_cselect_b32 vcc_lo, s66, s72
	s_add_u32 s38, s38, 0x40080
	s_addc_u32 s39, s39, 0
	s_add_u32 s30, s72, 0x100
	s_addc_u32 s31, s73, 0
	s_mov_b32 vcc_hi, -2
	.p2align 8

; #define PG8_WAIT_V(n) asm volatile("s_waitcnt vmcnt(" #n ")" ::: "memory")
; #define PG8_BAR __builtin_amdgcn_s_barrier()
; template <class Epi, class Sched, bool ALIGN_EPI = false, bool SP2 = false>
; __device__ __forceinline__ void gemm_phase(PG8_LAS unsigned char* lds, const Gemm g, const Sched& S, const Epi& E) {
;     ...
;     f32x4 acc[2][2][4][2];
; #pragma unroll
;     for (int a = 0; a < 2; ++a)
; #pragma unroll
;         for (int b = 0; b < 2; ++b)
; #pragma unroll
;             for (int m = 0; m < 4; ++m)
; #pragma unroll
;                 for (int n = 0; n < 2; ++n) acc[a][b][m][n] = (f32x4){0.f, 0.f, 0.f, 0.f};
;     bf16x8 At[4][2], B0[2][2], B1[2][2];
;     const char* cA = (const char*)g.A + (size_t)cur.pm * tstep + (size_t)cur.seg * K * 2; const char* cB = (const char*)g.Bt + (size_t)cur.pn * tstepB + (size_t)cur.seg * K * 2;
;     if constexpr (SP2) {
;         PG8_STAGE(PG8_SB(0, 0), cB, voffB); PG8_STAGE(PG8_SB(0, 1), cB + hstepB, voffB); PG8_STAGE(PG8_SA(0, 0), cA, voffA); PG8_STAGE(PG8_SA(0, 1), cA + hstep, voffA);
;         if (wr == 1) PG8_BAR;
;         PG8_WAIT_V(2); PG8_BAR;
;         PG8_STAGE(PG8_SB(1, 0), cB + kstep, voffB); PG8_STAGE(PG8_SA(1, 0), cA + kstep, voffA); PG8_STAGE(PG8_SB(1, 1), cB + hstepB + kstep, voffB);
;         PG8_WAIT_V(6); PG8_BAR;
;     } else {
;         PG8_STAGE(PG8_SB(0, 0), cB, voffB); PG8_STAGE(PG8_SA(0, 0), cA, voffA); PG8_STAGE(PG8_SB(0, 1), cB + hstepB, voffB); PG8_STAGE(PG8_SA(0, 1), cA + hstep, voffA);
;         if (wr == 1) PG8_BAR;
;         PG8_WAIT_V(4); PG8_BAR;
;         PG8_STAGE(PG8_SB(1, 0), cB + kstep, voffB); PG8_STAGE(PG8_SA(1, 0), cA + kstep, voffA); PG8_STAGE(PG8_SB(1, 1), cB + hstepB + kstep, voffB);
;         PG8_WAIT_V(6); PG8_BAR;
;     }
;     for (;;) {
;         const bool has_next = S.next(ui + 1, nxt);
;         const char* nA = has_next ? (const char*)g.A + (size_t)nxt.pm * tstep + (size_t)nxt.seg * K * 2 : cA; const char* nB = has_next ? (const char*)g.Bt + (size_t)nxt.pn * tstepB + (size_t)nxt.seg * K * 2 : cB;
;         for (int t = 0; t < nt; t += 2) {
;             const bool last = (t == nt - 2);
;             const char* a1 = cA + (size_t)(t + 1) * kstep;
;             const char* a2 = last ? nA : cA + (size_t)(t + 2) * kstep; const char* b2 = last ? nB : cB + (size_t)(t + 2) * kstep;
;             const char* a3 = a2 + kstep; const char* b3 = b2 + kstep;
.LBB0_645:
	s_ashr_i32 s49, s48, 31
	s_lshl_b64 s[30:31], s[48:49], 19
	s_add_u32 s56, s86, s30
	s_addc_u32 s57, s87, s31
	s_and_b64 s[30:31], s[74:75], exec
	s_cselect_b32 s49, s57, s71
	s_cselect_b32 vcc_lo, s56, s70
	s_ashr_i32 s51, s50, 31
	s_lshl_b64 s[30:31], s[50:51], 19
	s_add_u32 s66, s92, s30
	s_addc_u32 s67, s93, s31
	s_and_b64 s[30:31], s[74:75], exec
	s_cselect_b32 s51, s67, s73
	s_cselect_b32 vcc_hi, s66, s72
	s_add_u32 s70, s70, 0x40080
	s_addc_u32 s71, s71, 0
	s_add_u32 s30, s72, 0x100
	v_mov_b32_e32 v2, 0
	s_addc_u32 s31, s73, 0
	s_mov_b32 s34, -2
	s_waitcnt lgkmcnt(0)
	v_mov_b32_e32 v3, v2
	v_mov_b32_e32 v4, v2
	v_mov_b32_e32 v5, v2
	v_mov_b32_e32 v6, v2
	v_mov_b32_e32 v7, v2
	v_mov_b32_e32 v8, v2
	v_mov_b32_e32 v9, v2
	v_mov_b32_e32 v18, v2
	v_mov_b32_e32 v19, v2
	v_mov_b32_e32 v20, v2
	v_mov_b32_e32 v21, v2
	v_mov_b32_e32 v22, v2
	v_mov_b32_e32 v23, v2
	v_mov_b32_e32 v24, v2
	v_mov_b32_e32 v25, v2
	v_mov_b32_e32 v34, v2
	v_mov_b32_e32 v35, v2
	v_mov_b32_e32 v36, v2
	v_mov_b32_e32 v37, v2
	v_mov_b32_e32 v38, v2
	v_mov_b32_e32 v39, v2
	v_mov_b32_e32 v40, v2
	v_mov_b32_e32 v41, v2
	v_mov_b32_e32 v50, v2
	v_mov_b32_e32 v51, v2
	v_mov_b32_e32 v52, v2
	v_mov_b32_e32 v53, v2
	v_mov_b32_e32 v54, v2
	v_mov_b32_e32 v55, v2
	v_mov_b32_e32 v56, v2
	v_mov_b32_e32 v57, v2
	v_mov_b32_e32 v10, v2
	v_mov_b32_e32 v11, v2
	v_mov_b32_e32 v12, v2
	v_mov_b32_e32 v13, v2
	v_mov_b32_e32 v14, v2
	v_mov_b32_e32 v15, v2
	v_mov_b32_e32 v16, v2
	v_mov_b32_e32 v17, v2
	v_mov_b32_e32 v26, v2
	v_mov_b32_e32 v27, v2
	v_mov_b32_e32 v28, v2
	v_mov_b32_e32 v29, v2
	v_mov_b32_e32 v30, v2
	v_mov_b32_e32 v31, v2
	v_mov_b32_e32 v32, v2
	v_mov_b32_e32 v33, v2
	v_mov_b32_e32 v42, v2
	v_mov_b32_e32 v43, v2
	v_mov_b32_e32 v44, v2
	v_mov_b32_e32 v45, v2
	v_mov_b32_e32 v46, v2
	v_mov_b32_e32 v47, v2
	v_mov_b32_e32 v48, v2
	v_mov_b32_e32 v49, v2
	v_mov_b32_e32 v58, v2
	v_mov_b32_e32 v59, v2
	v_mov_b32_e32 v60, v2
	v_mov_b32_e32 v61, v2
	v_mov_b32_e32 v62, v2
	v_mov_b32_e32 v63, v2
	v_mov_b32_e32 v64, v2
	v_mov_b32_e32 v65, v2
	v_mov_b32_e32 v68, v2
	v_mov_b32_e32 v69, v2
	v_mov_b32_e32 v70, v2
	v_mov_b32_e32 v71, v2
	v_mov_b32_e32 v72, v2
	v_mov_b32_e32 v73, v2
	v_mov_b32_e32 v74, v2
	v_mov_b32_e32 v75, v2
	v_mov_b32_e32 v84, v2
	v_mov_b32_e32 v85, v2
	v_mov_b32_e32 v86, v2
	v_mov_b32_e32 v87, v2
	v_mov_b32_e32 v88, v2
	v_mov_b32_e32 v89, v2
	v_mov_b32_e32 v90, v2
	v_mov_b32_e32 v91, v2
	v_mov_b32_e32 v100, v2
	v_mov_b32_e32 v101, v2
	v_mov_b32_e32 v102, v2
	v_mov_b32_e32 v103, v2
	v_mov_b32_e32 v104, v2
	v_mov_b32_e32 v105, v2
	v_mov_b32_e32 v106, v2
	v_mov_b32_e32 v107, v2
	v_mov_b32_e32 v116, v2
	v_mov_b32_e32 v117, v2
	v_mov_b32_e32 v118, v2
	v_mov_b32_e32 v119, v2
	v_mov_b32_e32 v120, v2
	v_mov_b32_e32 v121, v2
	v_mov_b32_e32 v122, v2
	v_mov_b32_e32 v123, v2
	v_mov_b32_e32 v76, v2
	v_mov_b32_e32 v77, v2
	v_mov_b32_e32 v78, v2
	v_mov_b32_e32 v79, v2
	v_mov_b32_e32 v80, v2
	v_mov_b32_e32 v81, v2
	v_mov_b32_e32 v82, v2
	v_mov_b32_e32 v83, v2
	v_mov_b32_e32 v92, v2
	v_mov_b32_e32 v93, v2
	v_mov_b32_e32 v94, v2
	v_mov_b32_e32 v95, v2
	v_mov_b32_e32 v96, v2
	v_mov_b32_e32 v97, v2
	v_mov_b32_e32 v98, v2
	v_mov_b32_e32 v99, v2
	v_mov_b32_e32 v108, v2
	v_mov_b32_e32 v109, v2
	v_mov_b32_e32 v110, v2
	v_mov_b32_e32 v111, v2
	v_mov_b32_e32 v112, v2
	v_mov_b32_e32 v113, v2
	v_mov_b32_e32 v114, v2
	v_mov_b32_e32 v115, v2
	v_mov_b32_e32 v124, v2
	v_mov_b32_e32 v125, v2
	v_mov_b32_e32 v126, v2
	v_mov_b32_e32 v127, v2
	v_mov_b32_e32 v128, v2
	v_mov_b32_e32 v129, v2
	v_mov_b32_e32 v130, v2
	v_mov_b32_e32 v131, v2
	.p2align 8

; template <class Epi, class Sched, bool ALIGN_EPI = false, bool SP2 = false>
; __device__ __forceinline__ void gemm_phase(PG8_LAS unsigned char* lds, const Gemm g, const Sched& S, const Epi& E) {
;     ...
;     for (;;) {
;         const bool has_next = S.next(ui + 1, nxt);
;         const char* nA = has_next ? (const char*)g.A + (size_t)nxt.pm * tstep + (size_t)nxt.seg * K * 2 : cA; const char* nB = has_next ? (const char*)g.Bt + (size_t)nxt.pn * tstepB + (size_t)nxt.seg * K * 2 : cB;
.LBB0_778:
	s_andn2_b64 vcc, exec, s[50:51]
	s_mov_b32 s37, s48
	s_mov_b32 s72, s46
	s_mov_b64 s[66:67], s[60:61]
	s_mov_b64 s[62:63], s[56:57]
	s_cbranch_vccz .LBB0_788
	.p2align 6

; #define PG8_WAIT_V(n) asm volatile("s_waitcnt vmcnt(" #n ")" ::: "memory")
; template <class Epi, class Sched, bool ALIGN_EPI = false, bool SP2 = false>
; __device__ __forceinline__ void gemm_phase(PG8_LAS unsigned char* lds, const Gemm g, const Sched& S, const Epi& E) {
;     ...
;     f32x4 acc[2][2][4][2];
; #pragma unroll
;     for (int a = 0; a < 2; ++a)
; #pragma unroll
;         for (int b = 0; b < 2; ++b)
; #pragma unroll
;             for (int m = 0; m < 4; ++m)
; #pragma unroll
;                 for (int n = 0; n < 2; ++n) acc[a][b][m][n] = (f32x4){0.f, 0.f, 0.f, 0.f};
;     bf16x8 At[4][2], B0[2][2], B1[2][2];
;     const char* cA = (const char*)g.A + (size_t)cur.pm * tstep + (size_t)cur.seg * K * 2; const char* cB = (const char*)g.Bt + (size_t)cur.pn * tstepB + (size_t)cur.seg * K * 2;
;     if constexpr (SP2) {
;         PG8_STAGE(PG8_SB(0, 0), cB, voffB); PG8_STAGE(PG8_SB(0, 1), cB + hstepB, voffB); PG8_STAGE(PG8_SA(0, 0), cA, voffA); PG8_STAGE(PG8_SA(0, 1), cA + hstep, voffA);
;         if (wr == 1) PG8_BAR;
;         PG8_WAIT_V(2); PG8_BAR;
;         PG8_STAGE(PG8_SB(1, 0), cB + kstep, voffB); PG8_STAGE(PG8_SA(1, 0), cA + kstep, voffA); PG8_STAGE(PG8_SB(1, 1), cB + hstepB + kstep, voffB);
;         PG8_WAIT_V(6); PG8_BAR;
;     } else {
;         PG8_STAGE(PG8_SB(0, 0), cB, voffB); PG8_STAGE(PG8_SA(0, 0), cA, voffA); PG8_STAGE(PG8_SB(0, 1), cB + hstepB, voffB); PG8_STAGE(PG8_SA(0, 1), cA + hstep, voffA);
;         if (wr == 1) PG8_BAR;
;         PG8_WAIT_V(4); PG8_BAR;
;         PG8_STAGE(PG8_SB(1, 0), cB + kstep, voffB); PG8_STAGE(PG8_SA(1, 0), cA + kstep, voffA); PG8_STAGE(PG8_SB(1, 1), cB + hstepB + kstep, voffB);
;         PG8_WAIT_V(6); PG8_BAR;
;     }
;     for (;;) {
;         const bool has_next = S.next(ui + 1, nxt);
;         const char* nA = has_next ? (const char*)g.A + (size_t)nxt.pm * tstep + (size_t)nxt.seg * K * 2 : cA; const char* nB = has_next ? (const char*)g.Bt + (size_t)nxt.pn * tstepB + (size_t)nxt.seg * K * 2 : cB;
;         for (int t = 0; t < nt; t += 2) {
;             const bool last = (t == nt - 2);
;             const char* a1 = cA + (size_t)(t + 1) * kstep;
;             const char* a2 = last ? nA : cA + (size_t)(t + 2) * kstep; const char* b2 = last ? nB : cB + (size_t)(t + 2) * kstep;
;             const char* a3 = a2 + kstep; const char* b3 = b2 + kstep;
;             if constexpr (SP2) {
.LBB0_781:
	s_ashr_i32 s47, s46, 31
	s_lshl_b64 s[30:31], s[46:47], 19
	s_add_u32 s56, s90, s30
	s_addc_u32 s57, s91, s31
	s_and_b64 s[30:31], s[50:51], exec
	s_cselect_b32 s47, s57, s63
	s_cselect_b32 s73, s56, s62
	s_ashr_i32 s49, s48, 31
	s_lshl_b64 s[30:31], s[48:49], 19
	s_add_u32 s60, s58, s30
	s_addc_u32 s61, s59, s31
	s_and_b64 s[30:31], s[50:51], exec
	s_cselect_b32 s49, s61, s67
	s_cselect_b32 s74, s60, s66
	s_add_u32 s62, s62, 0x40080
	s_addc_u32 s63, s63, 0
	s_add_u32 s30, s66, 0x100
	v_mov_b32_e32 v2, 0
	s_addc_u32 s31, s67, 0
	s_mov_b32 s34, -2
	v_mov_b32_e32 v3, v2
	v_mov_b32_e32 v4, v2
	v_mov_b32_e32 v5, v2
	v_mov_b32_e32 v10, v2
	v_mov_b32_e32 v11, v2
	v_mov_b32_e32 v12, v2
	v_mov_b32_e32 v13, v2
	v_mov_b32_e32 v18, v2
	v_mov_b32_e32 v19, v2
	v_mov_b32_e32 v20, v2
	v_mov_b32_e32 v21, v2
	v_mov_b32_e32 v26, v2
	v_mov_b32_e32 v27, v2
	v_mov_b32_e32 v28, v2
	v_mov_b32_e32 v29, v2
	v_mov_b32_e32 v34, v2
	v_mov_b32_e32 v35, v2
	v_mov_b32_e32 v36, v2
	v_mov_b32_e32 v37, v2
	v_mov_b32_e32 v42, v2
	v_mov_b32_e32 v43, v2
	v_mov_b32_e32 v44, v2
	v_mov_b32_e32 v45, v2
	v_mov_b32_e32 v50, v2
	v_mov_b32_e32 v51, v2
	v_mov_b32_e32 v52, v2
	v_mov_b32_e32 v53, v2
	v_mov_b32_e32 v58, v2
	v_mov_b32_e32 v59, v2
	v_mov_b32_e32 v60, v2
	v_mov_b32_e32 v61, v2
	v_mov_b32_e32 v6, v2
	v_mov_b32_e32 v7, v2
	v_mov_b32_e32 v8, v2
	v_mov_b32_e32 v9, v2
	v_mov_b32_e32 v14, v2
	v_mov_b32_e32 v15, v2
	v_mov_b32_e32 v16, v2
	v_mov_b32_e32 v17, v2
	v_mov_b32_e32 v22, v2
	v_mov_b32_e32 v23, v2
	v_mov_b32_e32 v24, v2
	v_mov_b32_e32 v25, v2
	v_mov_b32_e32 v30, v2
	v_mov_b32_e32 v31, v2
	v_mov_b32_e32 v32, v2
	v_mov_b32_e32 v33, v2
	v_mov_b32_e32 v38, v2
	v_mov_b32_e32 v39, v2
	v_mov_b32_e32 v40, v2
	v_mov_b32_e32 v41, v2
	v_mov_b32_e32 v46, v2
	v_mov_b32_e32 v47, v2
	v_mov_b32_e32 v48, v2
	v_mov_b32_e32 v49, v2
	v_mov_b32_e32 v54, v2
	v_mov_b32_e32 v55, v2
	v_mov_b32_e32 v56, v2
	v_mov_b32_e32 v57, v2
	v_mov_b32_e32 v62, v2
	v_mov_b32_e32 v63, v2
	v_mov_b32_e32 v64, v2
	v_mov_b32_e32 v65, v2
	v_mov_b32_e32 v68, v2
	v_mov_b32_e32 v69, v2
	v_mov_b32_e32 v70, v2
	v_mov_b32_e32 v71, v2
	v_mov_b32_e32 v76, v2
	v_mov_b32_e32 v77, v2
	v_mov_b32_e32 v78, v2
	v_mov_b32_e32 v79, v2
	v_mov_b32_e32 v84, v2
	v_mov_b32_e32 v85, v2
	v_mov_b32_e32 v86, v2
	v_mov_b32_e32 v87, v2
	v_mov_b32_e32 v92, v2
	v_mov_b32_e32 v93, v2
	v_mov_b32_e32 v94, v2
	v_mov_b32_e32 v95, v2
	v_mov_b32_e32 v100, v2
	v_mov_b32_e32 v101, v2
	v_mov_b32_e32 v102, v2
	v_mov_b32_e32 v103, v2
	v_mov_b32_e32 v108, v2
	v_mov_b32_e32 v109, v2
	v_mov_b32_e32 v110, v2
	v_mov_b32_e32 v111, v2
	v_mov_b32_e32 v116, v2
	v_mov_b32_e32 v117, v2
	v_mov_b32_e32 v118, v2
	v_mov_b32_e32 v119, v2
	v_mov_b32_e32 v124, v2
	v_mov_b32_e32 v125, v2
	v_mov_b32_e32 v126, v2
	v_mov_b32_e32 v127, v2
	v_mov_b32_e32 v72, v2
	v_mov_b32_e32 v73, v2
	v_mov_b32_e32 v74, v2
	v_mov_b32_e32 v75, v2
	v_mov_b32_e32 v80, v2
	v_mov_b32_e32 v81, v2
	v_mov_b32_e32 v82, v2
	v_mov_b32_e32 v83, v2
	v_mov_b32_e32 v88, v2
	v_mov_b32_e32 v89, v2
	v_mov_b32_e32 v90, v2
	v_mov_b32_e32 v91, v2
	v_mov_b32_e32 v96, v2
	v_mov_b32_e32 v97, v2
	v_mov_b32_e32 v98, v2
	v_mov_b32_e32 v99, v2
	v_mov_b32_e32 v104, v2
	v_mov_b32_e32 v105, v2
	v_mov_b32_e32 v106, v2
	v_mov_b32_e32 v107, v2
	v_mov_b32_e32 v112, v2
	v_mov_b32_e32 v113, v2
	v_mov_b32_e32 v114, v2
	v_mov_b32_e32 v115, v2
	v_mov_b32_e32 v120, v2
	v_mov_b32_e32 v121, v2
	v_mov_b32_e32 v122, v2
	v_mov_b32_e32 v123, v2
	v_mov_b32_e32 v128, v2
	v_mov_b32_e32 v129, v2
	v_mov_b32_e32 v130, v2
	v_mov_b32_e32 v131, v2
	.p2align 8
.LBB0_782:
	s_add_u32 s35, s62, 0xfffc0080
	s_addc_u32 s66, s63, -1
	s_add_i32 s75, 0, 0x10000
	s_cmp_eq_u32 s34, 12
	s_cselect_b32 s71, s47, s66
	s_cselect_b32 s70, s73, s35
	s_cselect_b32 s67, s49, s31
	s_cselect_b32 s66, s74, s30
	s_add_i32 s35, 0, 0x14000
	v_add_u32_e32 v164, s75, v144
	v_add_u32_e32 v180, s35, v144
	ds_read_b128 v[148:151], v164
	ds_read_b128 v[152:155], v164 offset:1024
	ds_read_b128 v[156:159], v164 offset:2048
	ds_read_b128 v[164:167], v164 offset:3072
	ds_read_b128 v[168:171], v180
	ds_read_b128 v[172:175], v180 offset:1024
	ds_read_b128 v[176:179], v180 offset:2048
	ds_read_b128 v[180:183], v180 offset:3072
	v_lshl_add_u64 v[192:193], s[62:63], 0, v[140:141]
	s_add_i32 m0, s24, 0xc000
	ds_read_b128 v[184:187], v147
	ds_read_b128 v[188:191], v147 offset:1024
	ds_read_b128 v[204:207], v147 offset:2048
	ds_read_b128 v[208:211], v147 offset:3072
	ds_read_b128 v[212:215], v147 offset:4096
	ds_read_b128 v[216:219], v147 offset:5120
	ds_read_b128 v[220:223], v147 offset:6144
	ds_read_b128 v[224:227], v147 offset:7168
	global_load_lds_dwordx4 v[192:193], off
	v_lshl_add_u64 v[192:193], s[62:63], 0, v[142:143]
	s_add_i32 m0, s24, 0xe000
	s_nop 0
	global_load_lds_dwordx4 v[192:193], off
	s_waitcnt vmcnt(8)
	s_waitcnt lgkmcnt(0)
	s_barrier
; #define PG8_STAGE(bufoff, gbase, voff) do { _Pragma("unroll") for (int _i = 0; _i < 2; ++_i) \
;         __builtin_amdgcn_global_load_lds((const unsigned*)((const char*)(gbase) + (voff)[_i]), (PG8_LAS unsigned*)(lds + (bufoff) + ldsw + _i * 8192), 16, 0, 0); } while (0)
; #define PG8_LDA(dst, b, h) do { _Pragma("unroll") for (int m = 0; m < 4; ++m) _Pragma("unroll") for (int k = 0; k < 2; ++k) dst[m][k] = *(const PG8_LAS bf16x8*)(lds + PG8_SA(b, h) + aoff + m * 2048 + k * 1024); } while (0)
; #define PG8_MMA(ai, bj, At, Bt) do { __builtin_amdgcn_s_setprio(1); _Pragma("unroll") for (int m = 0; m < 4; ++m) _Pragma("unroll") for (int n = 0; n < 2; ++n) _Pragma("unroll") for (int k = 0; k < 2; ++k) \
;         acc[ai][bj][m][n] = __builtin_amdgcn_mfma_f32_16x16x32_bf16(Bt[n][k], At[m][k], acc[ai][bj][m][n], 0, 0, 0); __builtin_amdgcn_s_setprio(0); } while (0)
; #define PG8_WAIT_V(n) asm volatile("s_waitcnt vmcnt(" #n ")" ::: "memory")
; #define PG8_WAIT_L(n) asm volatile("s_waitcnt lgkmcnt(" #n ")" ::: "memory")
; #define PG8_BAR __builtin_amdgcn_s_barrier()
; #define PG8_SCHED __builtin_amdgcn_sched_barrier(0)
; template <class Epi, class Sched, bool ALIGN_EPI = false, bool SP2 = false>
; __device__ __forceinline__ void gemm_phase(PG8_LAS unsigned char* lds, const Gemm g, const Sched& S, const Epi& E) {
;     ...
;             PG8_WAIT_V(8); PG8_WAIT_L(0); PG8_BAR; PG8_MMA(0, 0, At, B0); PG8_MMA(0, 1, At, B1); PG8_BAR; PG8_SCHED;
;             PG8_LDA(At, 0, 1); PG8_STAGE(PG8_SB(0, 0), b2, voffB); PG8_STAGE(PG8_SB(0, 1), b2 + hstepB, voffB); PG8_STAGE(PG8_SA(0, 0), a2, voffA);
;             PG8_WAIT_V(8); PG8_WAIT_L(0); PG8_BAR; PG8_MMA(1, 0, At, B0); PG8_MMA(1, 1, At, B1); PG8_BAR; PG8_SCHED;
	s_setprio 1
	s_waitcnt lgkmcnt(0)
	v_mfma_f32_16x16x32_bf16 v[128:131], v[148:151], v[184:187], v[128:131]
	v_mfma_f32_16x16x32_bf16 v[120:123], v[156:159], v[184:187], v[120:123]
	v_mfma_f32_16x16x32_bf16 v[112:115], v[148:151], v[204:207], v[112:115]
	v_mfma_f32_16x16x32_bf16 v[104:107], v[156:159], v[204:207], v[104:107]
	v_mfma_f32_16x16x32_bf16 v[96:99], v[148:151], v[212:215], v[96:99]
	v_mfma_f32_16x16x32_bf16 v[88:91], v[156:159], v[212:215], v[88:91]
	v_mfma_f32_16x16x32_bf16 v[80:83], v[148:151], v[220:223], v[80:83]
	v_mfma_f32_16x16x32_bf16 v[72:75], v[156:159], v[220:223], v[72:75]
	v_mfma_f32_16x16x32_bf16 v[128:131], v[152:155], v[188:191], v[128:131]
	v_mfma_f32_16x16x32_bf16 v[120:123], v[164:167], v[188:191], v[120:123]
	v_mfma_f32_16x16x32_bf16 v[112:115], v[152:155], v[208:211], v[112:115]
	v_mfma_f32_16x16x32_bf16 v[104:107], v[164:167], v[208:211], v[104:107]
	v_mfma_f32_16x16x32_bf16 v[96:99], v[152:155], v[216:219], v[96:99]
	v_mfma_f32_16x16x32_bf16 v[88:91], v[164:167], v[216:219], v[88:91]
	v_mfma_f32_16x16x32_bf16 v[80:83], v[152:155], v[224:227], v[80:83]
	v_mfma_f32_16x16x32_bf16 v[72:75], v[164:167], v[224:227], v[72:75]
	s_setprio 0
	s_setprio 1
	v_mfma_f32_16x16x32_bf16 v[124:127], v[168:171], v[184:187], v[124:127]
	v_mfma_f32_16x16x32_bf16 v[116:119], v[176:179], v[184:187], v[116:119]
	v_mfma_f32_16x16x32_bf16 v[108:111], v[168:171], v[204:207], v[108:111]
	v_mfma_f32_16x16x32_bf16 v[100:103], v[176:179], v[204:207], v[100:103]
	v_mfma_f32_16x16x32_bf16 v[92:95], v[168:171], v[212:215], v[92:95]
	v_mfma_f32_16x16x32_bf16 v[84:87], v[176:179], v[212:215], v[84:87]
	v_mfma_f32_16x16x32_bf16 v[76:79], v[168:171], v[220:223], v[76:79]
	v_mfma_f32_16x16x32_bf16 v[68:71], v[176:179], v[220:223], v[68:71]
	v_mfma_f32_16x16x32_bf16 v[124:127], v[172:175], v[188:191], v[124:127]
	v_mfma_f32_16x16x32_bf16 v[116:119], v[180:183], v[188:191], v[116:119]
	v_mfma_f32_16x16x32_bf16 v[108:111], v[172:175], v[208:211], v[108:111]
	v_mfma_f32_16x16x32_bf16 v[100:103], v[180:183], v[208:211], v[100:103]
	v_mfma_f32_16x16x32_bf16 v[92:95], v[172:175], v[216:219], v[92:95]
	v_mfma_f32_16x16x32_bf16 v[84:87], v[180:183], v[216:219], v[84:87]
	v_mfma_f32_16x16x32_bf16 v[76:79], v[172:175], v[224:227], v[76:79]
	v_mfma_f32_16x16x32_bf16 v[68:71], v[180:183], v[224:227], v[68:71]
	s_setprio 0
	s_barrier
	s_add_i32 s75, s75, s23
	v_lshl_add_u64 v[192:193], s[66:67], 0, v[136:137]
	s_mov_b32 m0, s75
	ds_read_b128 v[184:187], v147 offset:16384
	ds_read_b128 v[188:191], v147 offset:17408
	ds_read_b128 v[204:207], v147 offset:18432
	ds_read_b128 v[208:211], v147 offset:19456
	ds_read_b128 v[212:215], v147 offset:20480
	ds_read_b128 v[216:219], v147 offset:21504
	ds_read_b128 v[220:223], v147 offset:22528
	ds_read_b128 v[224:227], v147 offset:23552
	global_load_lds_dwordx4 v[192:193], off
	s_add_i32 m0, s75, 0x2000
	s_add_u32 s76, s66, 0x40000
	v_lshl_add_u64 v[228:229], s[66:67], 0, v[132:133]
	s_addc_u32 s77, s67, 0
	s_add_i32 s35, s35, s23
	global_load_lds_dwordx4 v[228:229], off
	v_lshl_add_u64 v[230:231], s[76:77], 0, v[136:137]
	s_mov_b32 m0, s35
	v_lshl_add_u64 v[232:233], s[70:71], 0, v[134:135]
	global_load_lds_dwordx4 v[230:231], off
	v_lshl_add_u64 v[230:231], s[76:77], 0, v[132:133]
	s_add_i32 m0, s35, 0x2000
	s_nop 0
	global_load_lds_dwordx4 v[230:231], off
	v_lshl_add_u64 v[230:231], s[70:71], 0, v[138:139]
	s_mov_b32 m0, s24
	s_nop 0
	global_load_lds_dwordx4 v[230:231], off
	s_mov_b32 m0, s25
	s_nop 0
	global_load_lds_dwordx4 v[232:233], off
	s_waitcnt vmcnt(8)
	s_waitcnt lgkmcnt(0)
	s_barrier
	s_setprio 1
	s_waitcnt lgkmcnt(0)
	v_mfma_f32_16x16x32_bf16 v[62:65], v[148:151], v[184:187], v[62:65]
	v_mfma_f32_16x16x32_bf16 v[54:57], v[156:159], v[184:187], v[54:57]
	v_mfma_f32_16x16x32_bf16 v[46:49], v[148:151], v[204:207], v[46:49]
	v_mfma_f32_16x16x32_bf16 v[38:41], v[156:159], v[204:207], v[38:41]
	v_mfma_f32_16x16x32_bf16 v[30:33], v[148:151], v[212:215], v[30:33]
	v_mfma_f32_16x16x32_bf16 v[22:25], v[156:159], v[212:215], v[22:25]
	v_mfma_f32_16x16x32_bf16 v[14:17], v[148:151], v[220:223], v[14:17]
	v_mfma_f32_16x16x32_bf16 v[6:9], v[156:159], v[220:223], v[6:9]
	v_mfma_f32_16x16x32_bf16 v[62:65], v[152:155], v[188:191], v[62:65]
	v_mfma_f32_16x16x32_bf16 v[54:57], v[164:167], v[188:191], v[54:57]
	v_mfma_f32_16x16x32_bf16 v[46:49], v[152:155], v[208:211], v[46:49]
	v_mfma_f32_16x16x32_bf16 v[38:41], v[164:167], v[208:211], v[38:41]
	v_mfma_f32_16x16x32_bf16 v[30:33], v[152:155], v[216:219], v[30:33]
	v_mfma_f32_16x16x32_bf16 v[22:25], v[164:167], v[216:219], v[22:25]
	v_mfma_f32_16x16x32_bf16 v[14:17], v[152:155], v[224:227], v[14:17]
	v_mfma_f32_16x16x32_bf16 v[6:9], v[164:167], v[224:227], v[6:9]
	s_setprio 0
	s_setprio 1
	v_mfma_f32_16x16x32_bf16 v[58:61], v[168:171], v[184:187], v[58:61]
	v_mfma_f32_16x16x32_bf16 v[50:53], v[176:179], v[184:187], v[50:53]
	v_mfma_f32_16x16x32_bf16 v[42:45], v[168:171], v[204:207], v[42:45]
	v_mfma_f32_16x16x32_bf16 v[34:37], v[176:179], v[204:207], v[34:37]
	v_mfma_f32_16x16x32_bf16 v[26:29], v[168:171], v[212:215], v[26:29]
	v_mfma_f32_16x16x32_bf16 v[18:21], v[176:179], v[212:215], v[18:21]
	v_mfma_f32_16x16x32_bf16 v[10:13], v[168:171], v[220:223], v[10:13]
	v_mfma_f32_16x16x32_bf16 v[2:5], v[176:179], v[220:223], v[2:5]
	v_mfma_f32_16x16x32_bf16 v[58:61], v[172:175], v[188:191], v[58:61]
	v_mfma_f32_16x16x32_bf16 v[50:53], v[180:183], v[188:191], v[50:53]
	v_mfma_f32_16x16x32_bf16 v[42:45], v[172:175], v[208:211], v[42:45]
	v_mfma_f32_16x16x32_bf16 v[34:37], v[180:183], v[208:211], v[34:37]
	v_mfma_f32_16x16x32_bf16 v[26:29], v[172:175], v[216:219], v[26:29]
	v_mfma_f32_16x16x32_bf16 v[18:21], v[180:183], v[216:219], v[18:21]
	v_mfma_f32_16x16x32_bf16 v[10:13], v[172:175], v[224:227], v[10:13]
	v_mfma_f32_16x16x32_bf16 v[2:5], v[180:183], v[224:227], v[2:5]
	s_setprio 0
	s_barrier
; #define PG8_STAGE(bufoff, gbase, voff) do { _Pragma("unroll") for (int _i = 0; _i < 2; ++_i) \
;         __builtin_amdgcn_global_load_lds((const unsigned*)((const char*)(gbase) + (voff)[_i]), (PG8_LAS unsigned*)(lds + (bufoff) + ldsw + _i * 8192), 16, 0, 0); } while (0)
; #define PG8_LDA(dst, b, h) do { _Pragma("unroll") for (int m = 0; m < 4; ++m) _Pragma("unroll") for (int k = 0; k < 2; ++k) dst[m][k] = *(const PG8_LAS bf16x8*)(lds + PG8_SA(b, h) + aoff + m * 2048 + k * 1024); } while (0)
; #define PG8_LDB(dst, b, h) do { _Pragma("unroll") for (int n = 0; n < 2; ++n) _Pragma("unroll") for (int k = 0; k < 2; ++k) dst[n][k] = *(const PG8_LAS bf16x8*)(lds + PG8_SB(b, h) + boff + n * 2048 + k * 1024); } while (0)
; #define PG8_MMA(ai, bj, At, Bt) do { __builtin_amdgcn_s_setprio(1); _Pragma("unroll") for (int m = 0; m < 4; ++m) _Pragma("unroll") for (int n = 0; n < 2; ++n) _Pragma("unroll") for (int k = 0; k < 2; ++k) \
;         acc[ai][bj][m][n] = __builtin_amdgcn_mfma_f32_16x16x32_bf16(Bt[n][k], At[m][k], acc[ai][bj][m][n], 0, 0, 0); __builtin_amdgcn_s_setprio(0); } while (0)
; #define PG8_WAIT_V(n) asm volatile("s_waitcnt vmcnt(" #n ")" ::: "memory")
; #define PG8_WAIT_L(n) asm volatile("s_waitcnt lgkmcnt(" #n ")" ::: "memory")
; #define PG8_BAR __builtin_amdgcn_s_barrier()
; #define PG8_SCHED __builtin_amdgcn_sched_barrier(0)
; template <class Epi, class Sched, bool ALIGN_EPI = false, bool SP2 = false>
; __device__ __forceinline__ void gemm_phase(PG8_LAS unsigned char* lds, const Gemm g, const Sched& S, const Epi& E) {
;     ...
;             PG8_LDB(B0, 1, 0); PG8_LDB(B1, 1, 1); PG8_SCHED; PG8_LDA(At, 1, 0); PG8_STAGE(PG8_SA(0, 1), a2 + hstep, voffA);
;             PG8_WAIT_V(8); PG8_WAIT_L(0); PG8_BAR; PG8_MMA(0, 0, At, B0); PG8_MMA(0, 1, At, B1); PG8_BAR; PG8_SCHED;
	s_add_i32 s35, 0, 0x18000
	s_add_i32 s75, 0, 0x1c000
	v_add_u32_e32 v164, s35, v144
	v_add_u32_e32 v180, s75, v144
	ds_read_b128 v[148:151], v164
	ds_read_b128 v[152:155], v164 offset:1024
	ds_read_b128 v[156:159], v164 offset:2048
	ds_read_b128 v[164:167], v164 offset:3072
	ds_read_b128 v[168:171], v180
	ds_read_b128 v[172:175], v180 offset:1024
	ds_read_b128 v[176:179], v180 offset:2048
	ds_read_b128 v[180:183], v180 offset:3072
	s_add_u32 s70, s70, 0x40000
	s_addc_u32 s71, s71, 0
	s_mov_b32 m0, s26
	v_lshl_add_u64 v[234:235], s[70:71], 0, v[138:139]
	ds_read_b128 v[184:187], v147 offset:32768
	ds_read_b128 v[188:191], v147 offset:33792
	ds_read_b128 v[204:207], v147 offset:34816
	ds_read_b128 v[208:211], v147 offset:35840
	ds_read_b128 v[212:215], v147 offset:36864
	ds_read_b128 v[216:219], v147 offset:37888
	ds_read_b128 v[220:223], v147 offset:38912
	ds_read_b128 v[224:227], v147 offset:39936
	global_load_lds_dwordx4 v[234:235], off
	v_lshl_add_u64 v[234:235], s[70:71], 0, v[134:135]
	s_mov_b32 m0, s27
	s_nop 0
	global_load_lds_dwordx4 v[234:235], off
	s_waitcnt vmcnt(8)
	s_waitcnt lgkmcnt(0)
	s_barrier
	s_setprio 1
	s_waitcnt lgkmcnt(0)
	v_mfma_f32_16x16x32_bf16 v[128:131], v[148:151], v[184:187], v[128:131]
	v_mfma_f32_16x16x32_bf16 v[120:123], v[156:159], v[184:187], v[120:123]
	v_mfma_f32_16x16x32_bf16 v[112:115], v[148:151], v[204:207], v[112:115]
	v_mfma_f32_16x16x32_bf16 v[104:107], v[156:159], v[204:207], v[104:107]
	v_mfma_f32_16x16x32_bf16 v[96:99], v[148:151], v[212:215], v[96:99]
	v_mfma_f32_16x16x32_bf16 v[88:91], v[156:159], v[212:215], v[88:91]
	v_mfma_f32_16x16x32_bf16 v[80:83], v[148:151], v[220:223], v[80:83]
	v_mfma_f32_16x16x32_bf16 v[72:75], v[156:159], v[220:223], v[72:75]
	v_mfma_f32_16x16x32_bf16 v[128:131], v[152:155], v[188:191], v[128:131]
	v_mfma_f32_16x16x32_bf16 v[120:123], v[164:167], v[188:191], v[120:123]
	v_mfma_f32_16x16x32_bf16 v[112:115], v[152:155], v[208:211], v[112:115]
	v_mfma_f32_16x16x32_bf16 v[104:107], v[164:167], v[208:211], v[104:107]
	v_mfma_f32_16x16x32_bf16 v[96:99], v[152:155], v[216:219], v[96:99]
	v_mfma_f32_16x16x32_bf16 v[88:91], v[164:167], v[216:219], v[88:91]
	v_mfma_f32_16x16x32_bf16 v[80:83], v[152:155], v[224:227], v[80:83]
	v_mfma_f32_16x16x32_bf16 v[72:75], v[164:167], v[224:227], v[72:75]
	s_setprio 0
	s_setprio 1
	v_mfma_f32_16x16x32_bf16 v[124:127], v[168:171], v[184:187], v[124:127]
	v_mfma_f32_16x16x32_bf16 v[116:119], v[176:179], v[184:187], v[116:119]
	v_mfma_f32_16x16x32_bf16 v[108:111], v[168:171], v[204:207], v[108:111]
	v_mfma_f32_16x16x32_bf16 v[100:103], v[176:179], v[204:207], v[100:103]
	v_mfma_f32_16x16x32_bf16 v[92:95], v[168:171], v[212:215], v[92:95]
	v_mfma_f32_16x16x32_bf16 v[84:87], v[176:179], v[212:215], v[84:87]
	v_mfma_f32_16x16x32_bf16 v[76:79], v[168:171], v[220:223], v[76:79]
	v_mfma_f32_16x16x32_bf16 v[68:71], v[176:179], v[220:223], v[68:71]
	v_mfma_f32_16x16x32_bf16 v[124:127], v[172:175], v[188:191], v[124:127]
	v_mfma_f32_16x16x32_bf16 v[116:119], v[180:183], v[188:191], v[116:119]
	v_mfma_f32_16x16x32_bf16 v[108:111], v[172:175], v[208:211], v[108:111]
	v_mfma_f32_16x16x32_bf16 v[100:103], v[180:183], v[208:211], v[100:103]
	v_mfma_f32_16x16x32_bf16 v[92:95], v[172:175], v[216:219], v[92:95]
	v_mfma_f32_16x16x32_bf16 v[84:87], v[180:183], v[216:219], v[84:87]
	v_mfma_f32_16x16x32_bf16 v[76:79], v[172:175], v[224:227], v[76:79]
	v_mfma_f32_16x16x32_bf16 v[68:71], v[180:183], v[224:227], v[68:71]
	s_setprio 0
	s_barrier
; #define PG8_STAGE(bufoff, gbase, voff) do { _Pragma("unroll") for (int _i = 0; _i < 2; ++_i) \
;         __builtin_amdgcn_global_load_lds((const unsigned*)((const char*)(gbase) + (voff)[_i]), (PG8_LAS unsigned*)(lds + (bufoff) + ldsw + _i * 8192), 16, 0, 0); } while (0)
; #define PG8_LDA(dst, b, h) do { _Pragma("unroll") for (int m = 0; m < 4; ++m) _Pragma("unroll") for (int k = 0; k < 2; ++k) dst[m][k] = *(const PG8_LAS bf16x8*)(lds + PG8_SA(b, h) + aoff + m * 2048 + k * 1024); } while (0)
; template <class Epi, class Sched, bool ALIGN_EPI = false, bool SP2 = false>
; __device__ __forceinline__ void gemm_phase(PG8_LAS unsigned char* lds, const Gemm g, const Sched& S, const Epi& E) {
;     ...
;             PG8_LDA(At, 1, 1); PG8_STAGE(PG8_SB(1, 0), b3, voffB); PG8_STAGE(PG8_SB(1, 1), b3 + hstepB, voffB); PG8_STAGE(PG8_SA(1, 0), a3, voffA);
;             PG8_WAIT_V(8); PG8_WAIT_L(0); PG8_BAR; PG8_MMA(1, 0, At, B0); PG8_MMA(1, 1, At, B1); PG8_BAR; PG8_SCHED;
;             } else {
;             PG8_LDB(B0, 0, 0); PG8_SCHED; PG8_LDA(At, 0, 0); PG8_STAGE(PG8_SA(1, 1), a1 + hstep, voffA);
;             PG8_WAIT_L(8); PG8_BAR; PG8_WAIT_L(0); PG8_MMA(0, 0, At, B0); PG8_BAR; PG8_SCHED;
;             PG8_LDB(B1, 0, 1); PG8_STAGE(PG8_SB(0, 0), b2, voffB);
;             PG8_BAR; PG8_WAIT_L(0); PG8_MMA(0, 1, At, B1); PG8_BAR;
;             PG8_LDA(At, 0, 1); PG8_STAGE(PG8_SA(0, 0), a2, voffA);
;             PG8_BAR; PG8_WAIT_L(0); PG8_MMA(1, 0, At, B0); PG8_BAR; PG8_SCHED;
;             PG8_STAGE(PG8_SB(0, 1), b2 + hstepB, voffB);
;             PG8_WAIT_V(6); PG8_BAR; PG8_MMA(1, 1, At, B1); PG8_BAR;
;             PG8_LDB(B0, 1, 0); PG8_SCHED; PG8_LDA(At, 1, 0); PG8_STAGE(PG8_SA(0, 1), a2 + hstep, voffA);
;             PG8_WAIT_L(8); PG8_BAR; PG8_WAIT_L(0); PG8_MMA(0, 0, At, B0); PG8_BAR; PG8_SCHED;
;             PG8_LDB(B1, 1, 1); PG8_STAGE(PG8_SB(1, 0), b3, voffB);
;             PG8_BAR; PG8_WAIT_L(0); PG8_MMA(0, 1, At, B1); PG8_BAR;
;             PG8_LDA(At, 1, 1); PG8_STAGE(PG8_SA(1, 0), a3, voffA);
;             PG8_BAR; PG8_WAIT_L(0); PG8_MMA(1, 0, At, B0); PG8_BAR; PG8_SCHED;
;             PG8_STAGE(PG8_SB(1, 1), b3 + hstepB, voffB);
;             PG8_WAIT_V(6); PG8_BAR; PG8_MMA(1, 1, At, B1); PG8_BAR;
;             }
;         }
;         if constexpr (ALIGN_EPI) { if (wr == 0) PG8_BAR; }
;         E(acc, cur, wr, wc, fr, fq);
	s_add_i32 s35, s35, s23
	v_lshl_add_u64 v[192:193], v[192:193], 0, s[52:53]
	s_mov_b32 m0, s35
	ds_read_b128 v[184:187], v147 offset:49152
	ds_read_b128 v[188:191], v147 offset:50176
	ds_read_b128 v[204:207], v147 offset:51200
	ds_read_b128 v[208:211], v147 offset:52224
	ds_read_b128 v[212:215], v147 offset:53248
	ds_read_b128 v[216:219], v147 offset:54272
	ds_read_b128 v[220:223], v147 offset:55296
	ds_read_b128 v[224:227], v147 offset:56320
	global_load_lds_dwordx4 v[192:193], off
	s_add_i32 m0, s35, 0x2000
	s_add_u32 s66, s66, 0x40080
	v_lshl_add_u64 v[192:193], v[228:229], 0, s[52:53]
	s_addc_u32 s67, s67, 0
	s_add_i32 s35, s75, s23
	global_load_lds_dwordx4 v[192:193], off
	v_lshl_add_u64 v[192:193], s[66:67], 0, v[136:137]
	s_mov_b32 m0, s35
	s_nop 0
	global_load_lds_dwordx4 v[192:193], off
	v_lshl_add_u64 v[192:193], s[66:67], 0, v[132:133]
	s_add_i32 m0, s35, 0x2000
	s_nop 0
	global_load_lds_dwordx4 v[192:193], off
	v_lshl_add_u64 v[192:193], v[230:231], 0, s[52:53]
	s_mov_b32 m0, s28
	s_nop 0
	global_load_lds_dwordx4 v[192:193], off
	v_lshl_add_u64 v[192:193], v[232:233], 0, s[52:53]
	s_mov_b32 m0, s29
	s_nop 0
	global_load_lds_dwordx4 v[192:193], off
	s_waitcnt vmcnt(8)
	s_waitcnt lgkmcnt(0)
	s_barrier
	s_setprio 1
	s_waitcnt lgkmcnt(0)
	v_mfma_f32_16x16x32_bf16 v[62:65], v[148:151], v[184:187], v[62:65]
	v_mfma_f32_16x16x32_bf16 v[54:57], v[156:159], v[184:187], v[54:57]
	v_mfma_f32_16x16x32_bf16 v[46:49], v[148:151], v[204:207], v[46:49]
	v_mfma_f32_16x16x32_bf16 v[38:41], v[156:159], v[204:207], v[38:41]
	v_mfma_f32_16x16x32_bf16 v[30:33], v[148:151], v[212:215], v[30:33]
	v_mfma_f32_16x16x32_bf16 v[22:25], v[156:159], v[212:215], v[22:25]
	v_mfma_f32_16x16x32_bf16 v[14:17], v[148:151], v[220:223], v[14:17]
	v_mfma_f32_16x16x32_bf16 v[6:9], v[156:159], v[220:223], v[6:9]
	v_mfma_f32_16x16x32_bf16 v[62:65], v[152:155], v[188:191], v[62:65]
	v_mfma_f32_16x16x32_bf16 v[54:57], v[164:167], v[188:191], v[54:57]
	v_mfma_f32_16x16x32_bf16 v[46:49], v[152:155], v[208:211], v[46:49]
	v_mfma_f32_16x16x32_bf16 v[38:41], v[164:167], v[208:211], v[38:41]
	v_mfma_f32_16x16x32_bf16 v[30:33], v[152:155], v[216:219], v[30:33]
	v_mfma_f32_16x16x32_bf16 v[22:25], v[164:167], v[216:219], v[22:25]
	v_mfma_f32_16x16x32_bf16 v[14:17], v[152:155], v[224:227], v[14:17]
	v_mfma_f32_16x16x32_bf16 v[6:9], v[164:167], v[224:227], v[6:9]
	s_setprio 0
	s_setprio 1
	v_mfma_f32_16x16x32_bf16 v[58:61], v[168:171], v[184:187], v[58:61]
	v_mfma_f32_16x16x32_bf16 v[50:53], v[176:179], v[184:187], v[50:53]
	v_mfma_f32_16x16x32_bf16 v[42:45], v[168:171], v[204:207], v[42:45]
	v_mfma_f32_16x16x32_bf16 v[34:37], v[176:179], v[204:207], v[34:37]
	v_mfma_f32_16x16x32_bf16 v[26:29], v[168:171], v[212:215], v[26:29]
	v_mfma_f32_16x16x32_bf16 v[18:21], v[176:179], v[212:215], v[18:21]
	v_mfma_f32_16x16x32_bf16 v[10:13], v[168:171], v[220:223], v[10:13]
	v_mfma_f32_16x16x32_bf16 v[2:5], v[176:179], v[220:223], v[2:5]
	v_mfma_f32_16x16x32_bf16 v[58:61], v[172:175], v[188:191], v[58:61]
	v_mfma_f32_16x16x32_bf16 v[50:53], v[180:183], v[188:191], v[50:53]
	v_mfma_f32_16x16x32_bf16 v[42:45], v[172:175], v[208:211], v[42:45]
	v_mfma_f32_16x16x32_bf16 v[34:37], v[180:183], v[208:211], v[34:37]
	v_mfma_f32_16x16x32_bf16 v[26:29], v[172:175], v[216:219], v[26:29]
	v_mfma_f32_16x16x32_bf16 v[18:21], v[180:183], v[216:219], v[18:21]
	v_mfma_f32_16x16x32_bf16 v[10:13], v[172:175], v[224:227], v[10:13]
	v_mfma_f32_16x16x32_bf16 v[2:5], v[180:183], v[224:227], v[2:5]
	s_setprio 0
	s_barrier
	s_add_i32 s34, s34, 2
	s_add_u32 s62, s62, 0x100
	s_addc_u32 s63, s63, 0
	s_add_u32 s30, s30, 0x100
	s_addc_u32 s31, s31, 0
	s_cmp_gt_u32 s34, 13
	s_cbranch_scc0 .LBB0_782
	s_and_b64 vcc, exec, s[44:45]
	s_cbranch_vccz .LBB0_785
	s_barrier
	.p2align 6

; #define PG8_WAIT_V(n) asm volatile("s_waitcnt vmcnt(" #n ")" ::: "memory")
; #define PG8_BAR __builtin_amdgcn_s_barrier()
; template <class Epi, class Sched, bool ALIGN_EPI = false, bool SP2 = false>
; __device__ __forceinline__ void gemm_phase(PG8_LAS unsigned char* lds, const Gemm g, const Sched& S, const Epi& E) {
;     ...
;     f32x4 acc[2][2][4][2];
; #pragma unroll
;     for (int a = 0; a < 2; ++a)
; #pragma unroll
;         for (int b = 0; b < 2; ++b)
; #pragma unroll
;             for (int m = 0; m < 4; ++m)
; #pragma unroll
;                 for (int n = 0; n < 2; ++n) acc[a][b][m][n] = (f32x4){0.f, 0.f, 0.f, 0.f};
;     bf16x8 At[4][2], B0[2][2], B1[2][2];
;     const char* cA = (const char*)g.A + (size_t)cur.pm * tstep + (size_t)cur.seg * K * 2; const char* cB = (const char*)g.Bt + (size_t)cur.pn * tstepB + (size_t)cur.seg * K * 2;
;     if constexpr (SP2) {
;         PG8_STAGE(PG8_SB(0, 0), cB, voffB); PG8_STAGE(PG8_SB(0, 1), cB + hstepB, voffB); PG8_STAGE(PG8_SA(0, 0), cA, voffA); PG8_STAGE(PG8_SA(0, 1), cA + hstep, voffA);
;         if (wr == 1) PG8_BAR;
;         PG8_WAIT_V(2); PG8_BAR;
;         PG8_STAGE(PG8_SB(1, 0), cB + kstep, voffB); PG8_STAGE(PG8_SA(1, 0), cA + kstep, voffA); PG8_STAGE(PG8_SB(1, 1), cB + hstepB + kstep, voffB);
;         PG8_WAIT_V(6); PG8_BAR;
;     } else {
;         PG8_STAGE(PG8_SB(0, 0), cB, voffB); PG8_STAGE(PG8_SA(0, 0), cA, voffA); PG8_STAGE(PG8_SB(0, 1), cB + hstepB, voffB); PG8_STAGE(PG8_SA(0, 1), cA + hstep, voffA);
;         if (wr == 1) PG8_BAR;
;         PG8_WAIT_V(4); PG8_BAR;
;         PG8_STAGE(PG8_SB(1, 0), cB + kstep, voffB); PG8_STAGE(PG8_SA(1, 0), cA + kstep, voffA); PG8_STAGE(PG8_SB(1, 1), cB + hstepB + kstep, voffB);
;         PG8_WAIT_V(6); PG8_BAR;
;     }
;     for (;;) {
;         const bool has_next = S.next(ui + 1, nxt);
;         const char* nA = has_next ? (const char*)g.A + (size_t)nxt.pm * tstep + (size_t)nxt.seg * K * 2 : cA; const char* nB = has_next ? (const char*)g.Bt + (size_t)nxt.pn * tstepB + (size_t)nxt.seg * K * 2 : cB;
;         for (int t = 0; t < nt; t += 2) {
;             const bool last = (t == nt - 2);
;             const char* a1 = cA + (size_t)(t + 1) * kstep;
;             const char* a2 = last ? nA : cA + (size_t)(t + 2) * kstep; const char* b2 = last ? nB : cB + (size_t)(t + 2) * kstep;
;             const char* a3 = a2 + kstep; const char* b3 = b2 + kstep;
.LBB0_911:
	s_add_u32 s30, s50, 0x100
	v_mov_b32_e32 v2, 0
	s_addc_u32 s31, s51, 0
	s_mov_b32 s34, -2
	s_waitcnt lgkmcnt(0)
	v_mov_b32_e32 v3, v2
	v_mov_b32_e32 v4, v2
	v_mov_b32_e32 v5, v2
	v_mov_b32_e32 v6, v2
	v_mov_b32_e32 v7, v2
	v_mov_b32_e32 v8, v2
	v_mov_b32_e32 v9, v2
	v_mov_b32_e32 v18, v2
	v_mov_b32_e32 v19, v2
	v_mov_b32_e32 v20, v2
	v_mov_b32_e32 v21, v2
	v_mov_b32_e32 v22, v2
	v_mov_b32_e32 v23, v2
	v_mov_b32_e32 v24, v2
	v_mov_b32_e32 v25, v2
	v_mov_b32_e32 v34, v2
	v_mov_b32_e32 v35, v2
	v_mov_b32_e32 v36, v2
	v_mov_b32_e32 v37, v2
	v_mov_b32_e32 v38, v2
	v_mov_b32_e32 v39, v2
	v_mov_b32_e32 v40, v2
	v_mov_b32_e32 v41, v2
	v_mov_b32_e32 v50, v2
	v_mov_b32_e32 v51, v2
	v_mov_b32_e32 v52, v2
	v_mov_b32_e32 v53, v2
	v_mov_b32_e32 v54, v2
	v_mov_b32_e32 v55, v2
	v_mov_b32_e32 v56, v2
	v_mov_b32_e32 v57, v2
	v_mov_b32_e32 v10, v2
	v_mov_b32_e32 v11, v2
	v_mov_b32_e32 v12, v2
	v_mov_b32_e32 v13, v2
	v_mov_b32_e32 v14, v2
	v_mov_b32_e32 v15, v2
	v_mov_b32_e32 v16, v2
	v_mov_b32_e32 v17, v2
	v_mov_b32_e32 v26, v2
	v_mov_b32_e32 v27, v2
	v_mov_b32_e32 v28, v2
	v_mov_b32_e32 v29, v2
	v_mov_b32_e32 v30, v2
	v_mov_b32_e32 v31, v2
	v_mov_b32_e32 v32, v2
	v_mov_b32_e32 v33, v2
	v_mov_b32_e32 v42, v2
	v_mov_b32_e32 v43, v2
	v_mov_b32_e32 v44, v2
	v_mov_b32_e32 v45, v2
	v_mov_b32_e32 v46, v2
	v_mov_b32_e32 v47, v2
	v_mov_b32_e32 v48, v2
	v_mov_b32_e32 v49, v2
	v_mov_b32_e32 v58, v2
	v_mov_b32_e32 v59, v2
	v_mov_b32_e32 v60, v2
	v_mov_b32_e32 v61, v2
	v_mov_b32_e32 v62, v2
	v_mov_b32_e32 v63, v2
	v_mov_b32_e32 v64, v2
	v_mov_b32_e32 v65, v2
	v_mov_b32_e32 v68, v2
	v_mov_b32_e32 v69, v2
	v_mov_b32_e32 v70, v2
	v_mov_b32_e32 v71, v2
	v_mov_b32_e32 v72, v2
	v_mov_b32_e32 v73, v2
	v_mov_b32_e32 v74, v2
	v_mov_b32_e32 v75, v2
	v_mov_b32_e32 v84, v2
	v_mov_b32_e32 v85, v2
	v_mov_b32_e32 v86, v2
	v_mov_b32_e32 v87, v2
	v_mov_b32_e32 v88, v2
	v_mov_b32_e32 v89, v2
	v_mov_b32_e32 v90, v2
	v_mov_b32_e32 v91, v2
	v_mov_b32_e32 v100, v2
	v_mov_b32_e32 v101, v2
	v_mov_b32_e32 v102, v2
	v_mov_b32_e32 v103, v2
	v_mov_b32_e32 v104, v2
	v_mov_b32_e32 v105, v2
	v_mov_b32_e32 v106, v2
	v_mov_b32_e32 v107, v2
	v_mov_b32_e32 v116, v2
	v_mov_b32_e32 v117, v2
	v_mov_b32_e32 v118, v2
	v_mov_b32_e32 v119, v2
	v_mov_b32_e32 v120, v2
	v_mov_b32_e32 v121, v2
	v_mov_b32_e32 v122, v2
	v_mov_b32_e32 v123, v2
	v_mov_b32_e32 v76, v2
	v_mov_b32_e32 v77, v2
	v_mov_b32_e32 v78, v2
	v_mov_b32_e32 v79, v2
	v_mov_b32_e32 v80, v2
	v_mov_b32_e32 v81, v2
	v_mov_b32_e32 v82, v2
	v_mov_b32_e32 v83, v2
	v_mov_b32_e32 v92, v2
	v_mov_b32_e32 v93, v2
	v_mov_b32_e32 v94, v2
	v_mov_b32_e32 v95, v2
	v_mov_b32_e32 v96, v2
	v_mov_b32_e32 v97, v2
	v_mov_b32_e32 v98, v2
	v_mov_b32_e32 v99, v2
	v_mov_b32_e32 v108, v2
	v_mov_b32_e32 v109, v2
	v_mov_b32_e32 v110, v2
	v_mov_b32_e32 v111, v2
	v_mov_b32_e32 v112, v2
	v_mov_b32_e32 v113, v2
	v_mov_b32_e32 v114, v2
	v_mov_b32_e32 v115, v2
	v_mov_b32_e32 v124, v2
	v_mov_b32_e32 v125, v2
	v_mov_b32_e32 v126, v2
	v_mov_b32_e32 v127, v2
	v_mov_b32_e32 v128, v2
	v_mov_b32_e32 v129, v2
	v_mov_b32_e32 v130, v2
	v_mov_b32_e32 v131, v2
	.p2align 8
